# nt hint on the merge GEMM's read-once gate loads (mid rescales and epilogue)
# speedup vs baseline: 1.0064x; 1.0064x over previous
.LBB0_3766:
	s_cmpk_eq_i32 s20, 0x1000
	s_cselect_b32 s22, 0, 16
	s_add_i32 s22, s53, s22
	v_mov_b32_e32 v2, v183
	v_mov_b32_e32 v4, v182
	s_ashr_i32 s23, s22, 31
	s_lshl_b64 s[22:23], s[22:23], 16
	v_lshl_add_u32 v2, v2, 4, v4
	s_add_u32 s24, s36, s22
	v_add_u32_e32 v4, s39, v2
	s_addc_u32 s25, s37, s23
	s_add_u32 s22, s24, 0x100000
	v_ashrrev_i32_e32 v5, 31, v4
	s_addc_u32 s23, s25, 0
	v_lshlrev_b64 v[134:135], 4, v[4:5]
	v_lshl_add_u64 v[136:137], s[24:25], 0, v[134:135]
	v_lshl_add_u64 v[134:135], s[22:23], 0, v[134:135]
	global_load_dwordx4 v[158:161], v[136:137], off nt
	global_load_dwordx4 v[162:165], v[134:135], off nt
	v_add_u32_e32 v4, 0x200, v4
	v_ashrrev_i32_e32 v5, 31, v4
	v_lshlrev_b64 v[4:5], 4, v[4:5]
	v_lshl_add_u64 v[134:135], s[24:25], 0, v[4:5]
	v_lshl_add_u64 v[4:5], s[22:23], 0, v[4:5]
	global_load_dwordx4 v[150:153], v[134:135], off nt
	global_load_dwordx4 v[154:157], v[4:5], off nt
	v_add_u32_e32 v4, s40, v2
	v_ashrrev_i32_e32 v5, 31, v4
	v_lshlrev_b64 v[4:5], 4, v[4:5]
	v_lshl_add_u64 v[134:135], s[24:25], 0, v[4:5]
	v_lshl_add_u64 v[4:5], s[22:23], 0, v[4:5]
	global_load_dwordx4 v[142:145], v[134:135], off nt
	global_load_dwordx4 v[146:149], v[4:5], off nt
	v_add_u32_e32 v4, s42, v2
	v_ashrrev_i32_e32 v5, 31, v4
	v_lshlrev_b64 v[4:5], 4, v[4:5]
	v_lshl_add_u64 v[134:135], s[24:25], 0, v[4:5]
	v_lshl_add_u64 v[4:5], s[22:23], 0, v[4:5]
	global_load_dwordx4 v[134:137], v[134:135], off nt
	s_andn2_b64 vcc, exec, s[8:9]
	global_load_dwordx4 v[138:141], v[4:5], off nt
	s_waitcnt vmcnt(0)
	v_cvt_f32_ubyte1_e32 v191, v158
	v_cvt_f32_ubyte0_e32 v4, v162
	v_cvt_f32_ubyte1_e32 v5, v162
	v_rcp_iflag_f32_e32 v4, v4
	v_rcp_iflag_f32_e32 v5, v5
	v_cvt_f32_ubyte0_e32 v190, v158
	v_cvt_f32_ubyte2_e32 v186, v162
	v_cvt_f32_ubyte3_e32 v162, v162
	v_pk_mul_f32 v[4:5], v[4:5], v[190:191]
	v_rcp_iflag_f32_e32 v186, v186
	v_rcp_iflag_f32_e32 v187, v162
	v_pk_mul_f32 v[130:131], v[130:131], v[4:5]
	v_cvt_f32_ubyte0_e32 v4, v163
	v_cvt_f32_ubyte1_e32 v5, v163
	v_rcp_iflag_f32_e32 v4, v4
	v_rcp_iflag_f32_e32 v5, v5
	v_cvt_f32_ubyte3_e32 v189, v158
	v_cvt_f32_ubyte2_e32 v188, v158
	v_cvt_f32_ubyte2_e32 v158, v163
	v_pk_mul_f32 v[186:187], v[186:187], v[188:189]
	v_rcp_iflag_f32_e32 v162, v158
	v_cvt_f32_ubyte3_e32 v158, v163
	v_cvt_f32_ubyte1_e32 v189, v159
	v_cvt_f32_ubyte0_e32 v188, v159
	v_rcp_iflag_f32_e32 v163, v158
	v_pk_mul_f32 v[4:5], v[4:5], v[188:189]
	v_pk_mul_f32 v[132:133], v[132:133], v[186:187]
	v_pk_mul_f32 v[126:127], v[126:127], v[4:5]
	v_cvt_f32_ubyte0_e32 v4, v164
	v_cvt_f32_ubyte1_e32 v5, v164
	v_rcp_iflag_f32_e32 v4, v4
	v_rcp_iflag_f32_e32 v5, v5
	v_cvt_f32_ubyte3_e32 v187, v159
	v_cvt_f32_ubyte2_e32 v186, v159
	v_pk_mul_f32 v[158:159], v[162:163], v[186:187]
	v_cvt_f32_ubyte1_e32 v187, v160
	v_pk_mul_f32 v[128:129], v[128:129], v[158:159]
	v_cvt_f32_ubyte2_e32 v158, v164
	v_cvt_f32_ubyte3_e32 v159, v164
	v_cvt_f32_ubyte0_e32 v186, v160
	v_rcp_iflag_f32_e32 v158, v158
	v_rcp_iflag_f32_e32 v159, v159
	v_pk_mul_f32 v[4:5], v[4:5], v[186:187]
	v_cvt_f32_ubyte3_e32 v163, v160
	v_pk_mul_f32 v[122:123], v[122:123], v[4:5]
	v_cvt_f32_ubyte0_e32 v4, v165
	v_cvt_f32_ubyte1_e32 v5, v165
	v_rcp_iflag_f32_e32 v4, v4
	v_rcp_iflag_f32_e32 v5, v5
	v_cvt_f32_ubyte2_e32 v162, v160
	v_pk_mul_f32 v[158:159], v[158:159], v[162:163]
	v_cvt_f32_ubyte0_e32 v164, v161
	v_pk_mul_f32 v[124:125], v[124:125], v[158:159]
	v_cvt_f32_ubyte2_e32 v158, v165
	v_cvt_f32_ubyte3_e32 v159, v165
	v_cvt_f32_ubyte1_e32 v165, v161
	v_pk_mul_f32 v[4:5], v[4:5], v[164:165]
	v_rcp_iflag_f32_e32 v158, v158
	v_rcp_iflag_f32_e32 v159, v159
	v_pk_mul_f32 v[118:119], v[118:119], v[4:5]
	v_cvt_f32_ubyte0_e32 v4, v154
	v_cvt_f32_ubyte1_e32 v5, v154
	v_rcp_iflag_f32_e32 v4, v4
	v_rcp_iflag_f32_e32 v5, v5
	v_cvt_f32_ubyte3_e32 v163, v161
	v_cvt_f32_ubyte2_e32 v162, v161
	v_pk_mul_f32 v[158:159], v[158:159], v[162:163]
	v_cvt_f32_ubyte1_e32 v163, v150
	v_cvt_f32_ubyte0_e32 v162, v150
	v_pk_mul_f32 v[120:121], v[120:121], v[158:159]
	v_cvt_f32_ubyte2_e32 v158, v154
	v_cvt_f32_ubyte3_e32 v154, v154
	v_pk_mul_f32 v[4:5], v[4:5], v[162:163]
	v_rcp_iflag_f32_e32 v158, v158
	v_rcp_iflag_f32_e32 v159, v154
	v_pk_mul_f32 v[114:115], v[114:115], v[4:5]
	v_cvt_f32_ubyte0_e32 v4, v155
	v_cvt_f32_ubyte1_e32 v5, v155
	v_rcp_iflag_f32_e32 v4, v4
	v_rcp_iflag_f32_e32 v5, v5
	v_cvt_f32_ubyte3_e32 v161, v150
	v_cvt_f32_ubyte2_e32 v160, v150
	v_cvt_f32_ubyte2_e32 v150, v155
	v_rcp_iflag_f32_e32 v154, v150
	v_cvt_f32_ubyte3_e32 v150, v155
	v_pk_mul_f32 v[158:159], v[158:159], v[160:161]
	v_rcp_iflag_f32_e32 v155, v150
	v_cvt_f32_ubyte1_e32 v161, v151
	v_cvt_f32_ubyte0_e32 v160, v151
	v_pk_mul_f32 v[4:5], v[4:5], v[160:161]
	v_pk_mul_f32 v[116:117], v[116:117], v[158:159]
	v_pk_mul_f32 v[110:111], v[110:111], v[4:5]
	v_cvt_f32_ubyte0_e32 v4, v156
	v_cvt_f32_ubyte1_e32 v5, v156
	v_cvt_f32_ubyte3_e32 v159, v151
	v_cvt_f32_ubyte2_e32 v158, v151
	v_rcp_iflag_f32_e32 v4, v4
	v_rcp_iflag_f32_e32 v5, v5
	v_pk_mul_f32 v[150:151], v[154:155], v[158:159]
	v_cvt_f32_ubyte1_e32 v159, v152
	v_pk_mul_f32 v[112:113], v[112:113], v[150:151]
	v_cvt_f32_ubyte2_e32 v150, v156
	v_cvt_f32_ubyte3_e32 v151, v156
	v_rcp_iflag_f32_e32 v150, v150
	v_rcp_iflag_f32_e32 v151, v151
	v_cvt_f32_ubyte0_e32 v158, v152
	v_pk_mul_f32 v[4:5], v[4:5], v[158:159]
	v_cvt_f32_ubyte3_e32 v155, v152
	v_pk_mul_f32 v[106:107], v[106:107], v[4:5]
	v_cvt_f32_ubyte0_e32 v4, v157
	v_cvt_f32_ubyte1_e32 v5, v157
	v_cvt_f32_ubyte2_e32 v154, v152
	v_rcp_iflag_f32_e32 v4, v4
	v_rcp_iflag_f32_e32 v5, v5
	v_pk_mul_f32 v[150:151], v[150:151], v[154:155]
	v_cvt_f32_ubyte0_e32 v156, v153
	v_pk_mul_f32 v[108:109], v[108:109], v[150:151]
	v_cvt_f32_ubyte2_e32 v150, v157
	v_cvt_f32_ubyte3_e32 v151, v157
	v_rcp_iflag_f32_e32 v150, v150
	v_rcp_iflag_f32_e32 v151, v151
	v_cvt_f32_ubyte1_e32 v157, v153
	v_pk_mul_f32 v[4:5], v[4:5], v[156:157]
	v_cvt_f32_ubyte3_e32 v155, v153
	v_pk_mul_f32 v[102:103], v[102:103], v[4:5]
	v_add_u32_e32 v4, s43, v2
	v_cvt_f32_ubyte2_e32 v154, v153
	v_ashrrev_i32_e32 v5, 31, v4
	v_pk_mul_f32 v[150:151], v[150:151], v[154:155]
	v_lshlrev_b64 v[4:5], 4, v[4:5]
	v_pk_mul_f32 v[104:105], v[104:105], v[150:151]
	v_lshl_add_u64 v[150:151], s[24:25], 0, v[4:5]
	v_lshl_add_u64 v[4:5], s[22:23], 0, v[4:5]
	global_load_dwordx4 v[158:161], v[150:151], off nt
	global_load_dwordx4 v[162:165], v[4:5], off nt
	v_add_u32_e32 v4, s44, v2
	v_ashrrev_i32_e32 v5, 31, v4
	v_lshlrev_b64 v[4:5], 4, v[4:5]
	v_lshl_add_u64 v[150:151], s[24:25], 0, v[4:5]
	v_lshl_add_u64 v[4:5], s[22:23], 0, v[4:5]
	global_load_dwordx4 v[150:153], v[150:151], off nt
	v_cvt_f32_ubyte1_e32 v191, v142
	global_load_dwordx4 v[154:157], v[4:5], off nt
	v_cvt_f32_ubyte0_e32 v4, v146
	v_cvt_f32_ubyte1_e32 v5, v146
	v_rcp_iflag_f32_e32 v4, v4
	v_rcp_iflag_f32_e32 v5, v5
	v_cvt_f32_ubyte0_e32 v190, v142
	v_cvt_f32_ubyte2_e32 v186, v146
	v_cvt_f32_ubyte3_e32 v146, v146
	v_pk_mul_f32 v[4:5], v[4:5], v[190:191]
	v_rcp_iflag_f32_e32 v186, v186
	v_rcp_iflag_f32_e32 v187, v146
	v_pk_mul_f32 v[98:99], v[98:99], v[4:5]
	v_cvt_f32_ubyte0_e32 v4, v147
	v_cvt_f32_ubyte1_e32 v5, v147
	v_rcp_iflag_f32_e32 v4, v4
	v_rcp_iflag_f32_e32 v5, v5
	v_cvt_f32_ubyte3_e32 v189, v142
	v_cvt_f32_ubyte2_e32 v188, v142
	v_cvt_f32_ubyte2_e32 v142, v147
	v_pk_mul_f32 v[186:187], v[186:187], v[188:189]
	v_rcp_iflag_f32_e32 v146, v142
	v_cvt_f32_ubyte3_e32 v142, v147
	v_cvt_f32_ubyte1_e32 v189, v143
	v_cvt_f32_ubyte0_e32 v188, v143
	v_rcp_iflag_f32_e32 v147, v142
	v_pk_mul_f32 v[4:5], v[4:5], v[188:189]
	v_pk_mul_f32 v[100:101], v[100:101], v[186:187]
	v_pk_mul_f32 v[94:95], v[94:95], v[4:5]
	v_cvt_f32_ubyte0_e32 v4, v148
	v_cvt_f32_ubyte1_e32 v5, v148
	v_rcp_iflag_f32_e32 v4, v4
	v_rcp_iflag_f32_e32 v5, v5
	v_cvt_f32_ubyte3_e32 v187, v143
	v_cvt_f32_ubyte2_e32 v186, v143
	v_pk_mul_f32 v[142:143], v[146:147], v[186:187]
	v_cvt_f32_ubyte1_e32 v187, v144
	v_pk_mul_f32 v[96:97], v[96:97], v[142:143]
	v_cvt_f32_ubyte2_e32 v142, v148
	v_cvt_f32_ubyte3_e32 v143, v148
	v_cvt_f32_ubyte0_e32 v186, v144
	v_rcp_iflag_f32_e32 v142, v142
	v_rcp_iflag_f32_e32 v143, v143
	v_pk_mul_f32 v[4:5], v[4:5], v[186:187]
	v_cvt_f32_ubyte3_e32 v147, v144
	v_pk_mul_f32 v[90:91], v[90:91], v[4:5]
	v_cvt_f32_ubyte0_e32 v4, v149
	v_cvt_f32_ubyte1_e32 v5, v149
	v_rcp_iflag_f32_e32 v4, v4
	v_rcp_iflag_f32_e32 v5, v5
	v_cvt_f32_ubyte2_e32 v146, v144
	v_pk_mul_f32 v[142:143], v[142:143], v[146:147]
	v_cvt_f32_ubyte0_e32 v148, v145
	v_pk_mul_f32 v[92:93], v[92:93], v[142:143]
	v_cvt_f32_ubyte2_e32 v142, v149
	v_cvt_f32_ubyte3_e32 v143, v149
	v_cvt_f32_ubyte1_e32 v149, v145
	v_pk_mul_f32 v[4:5], v[4:5], v[148:149]
	v_rcp_iflag_f32_e32 v142, v142
	v_rcp_iflag_f32_e32 v143, v143
	v_pk_mul_f32 v[86:87], v[86:87], v[4:5]
	v_cvt_f32_ubyte0_e32 v4, v138
	v_cvt_f32_ubyte1_e32 v5, v138
	v_rcp_iflag_f32_e32 v4, v4
	v_rcp_iflag_f32_e32 v5, v5
	v_cvt_f32_ubyte3_e32 v147, v145
	v_cvt_f32_ubyte2_e32 v146, v145
	v_pk_mul_f32 v[142:143], v[142:143], v[146:147]
	v_cvt_f32_ubyte1_e32 v147, v134
	v_cvt_f32_ubyte0_e32 v146, v134
	v_pk_mul_f32 v[88:89], v[88:89], v[142:143]
	v_cvt_f32_ubyte2_e32 v142, v138
	v_cvt_f32_ubyte3_e32 v138, v138
	v_pk_mul_f32 v[4:5], v[4:5], v[146:147]
	v_rcp_iflag_f32_e32 v142, v142
	v_rcp_iflag_f32_e32 v143, v138
	v_pk_mul_f32 v[82:83], v[82:83], v[4:5]
	v_cvt_f32_ubyte0_e32 v4, v139
	v_cvt_f32_ubyte1_e32 v5, v139
	v_rcp_iflag_f32_e32 v4, v4
	v_rcp_iflag_f32_e32 v5, v5
	v_cvt_f32_ubyte3_e32 v145, v134
	v_cvt_f32_ubyte2_e32 v144, v134
	v_cvt_f32_ubyte2_e32 v134, v139
	v_rcp_iflag_f32_e32 v138, v134
	v_cvt_f32_ubyte3_e32 v134, v139
	v_pk_mul_f32 v[142:143], v[142:143], v[144:145]
	v_rcp_iflag_f32_e32 v139, v134
	v_cvt_f32_ubyte1_e32 v145, v135
	v_cvt_f32_ubyte0_e32 v144, v135
	v_pk_mul_f32 v[4:5], v[4:5], v[144:145]
	v_pk_mul_f32 v[84:85], v[84:85], v[142:143]
	v_pk_mul_f32 v[78:79], v[78:79], v[4:5]
	v_cvt_f32_ubyte0_e32 v4, v140
	v_cvt_f32_ubyte1_e32 v5, v140
	v_cvt_f32_ubyte3_e32 v143, v135
	v_cvt_f32_ubyte2_e32 v142, v135
	v_rcp_iflag_f32_e32 v4, v4
	v_rcp_iflag_f32_e32 v5, v5
	v_pk_mul_f32 v[134:135], v[138:139], v[142:143]
	v_cvt_f32_ubyte1_e32 v143, v136
	v_pk_mul_f32 v[80:81], v[80:81], v[134:135]
	v_cvt_f32_ubyte2_e32 v134, v140
	v_cvt_f32_ubyte3_e32 v135, v140
	v_rcp_iflag_f32_e32 v134, v134
	v_rcp_iflag_f32_e32 v135, v135
	v_cvt_f32_ubyte0_e32 v142, v136
	v_pk_mul_f32 v[4:5], v[4:5], v[142:143]
	v_cvt_f32_ubyte3_e32 v139, v136
	v_pk_mul_f32 v[74:75], v[74:75], v[4:5]
	v_cvt_f32_ubyte0_e32 v4, v141
	v_cvt_f32_ubyte1_e32 v5, v141
	v_cvt_f32_ubyte2_e32 v138, v136
	v_rcp_iflag_f32_e32 v4, v4
	v_rcp_iflag_f32_e32 v5, v5
	v_pk_mul_f32 v[134:135], v[134:135], v[138:139]
	v_cvt_f32_ubyte0_e32 v140, v137
	v_pk_mul_f32 v[76:77], v[76:77], v[134:135]
	v_cvt_f32_ubyte2_e32 v134, v141
	v_cvt_f32_ubyte3_e32 v135, v141
	v_rcp_iflag_f32_e32 v134, v134
	v_rcp_iflag_f32_e32 v135, v135
	v_cvt_f32_ubyte1_e32 v141, v137
	v_pk_mul_f32 v[4:5], v[4:5], v[140:141]
	v_cvt_f32_ubyte3_e32 v139, v137
	v_pk_mul_f32 v[70:71], v[70:71], v[4:5]
	v_add_u32_e32 v4, s45, v2
	v_cvt_f32_ubyte2_e32 v138, v137
	v_ashrrev_i32_e32 v5, 31, v4
	v_pk_mul_f32 v[134:135], v[134:135], v[138:139]
	v_lshlrev_b64 v[4:5], 4, v[4:5]
	v_pk_mul_f32 v[72:73], v[72:73], v[134:135]
	v_lshl_add_u64 v[134:135], s[24:25], 0, v[4:5]
	v_lshl_add_u64 v[4:5], s[22:23], 0, v[4:5]
	global_load_dwordx4 v[142:145], v[134:135], off nt
	global_load_dwordx4 v[146:149], v[4:5], off nt
	v_add_u32_e32 v4, s46, v2
	v_ashrrev_i32_e32 v5, 31, v4
	v_lshlrev_b64 v[4:5], 4, v[4:5]
	v_lshl_add_u64 v[134:135], s[24:25], 0, v[4:5]
	v_lshl_add_u64 v[4:5], s[22:23], 0, v[4:5]
	global_load_dwordx4 v[134:137], v[134:135], off nt
	s_waitcnt vmcnt(0)
	v_cvt_f32_ubyte0_e32 v2, v162
	global_load_dwordx4 v[138:141], v[4:5], off nt
	v_rcp_iflag_f32_e32 v4, v2
	v_cvt_f32_ubyte1_e32 v2, v162
	v_rcp_iflag_f32_e32 v5, v2
	v_cvt_f32_ubyte2_e32 v2, v162
	v_rcp_iflag_f32_e32 v186, v2
	v_cvt_f32_ubyte3_e32 v2, v162
	v_cvt_f32_ubyte1_e32 v191, v158
	v_cvt_f32_ubyte0_e32 v190, v158
	v_rcp_iflag_f32_e32 v187, v2
	v_pk_mul_f32 v[4:5], v[4:5], v[190:191]
	v_cvt_f32_ubyte0_e32 v2, v163
	v_pk_mul_f32 v[66:67], v[66:67], v[4:5]
	v_rcp_iflag_f32_e32 v4, v2
	v_cvt_f32_ubyte1_e32 v2, v163
	v_rcp_iflag_f32_e32 v5, v2
	v_cvt_f32_ubyte3_e32 v189, v158
	v_cvt_f32_ubyte2_e32 v188, v158
	v_cvt_f32_ubyte2_e32 v2, v163
	v_pk_mul_f32 v[186:187], v[186:187], v[188:189]
	v_rcp_iflag_f32_e32 v162, v2
	v_cvt_f32_ubyte3_e32 v2, v163
	v_cvt_f32_ubyte1_e32 v189, v159
	v_cvt_f32_ubyte0_e32 v188, v159
	v_rcp_iflag_f32_e32 v163, v2
	v_pk_mul_f32 v[4:5], v[4:5], v[188:189]
	v_cvt_f32_ubyte0_e32 v2, v164
	v_pk_mul_f32 v[62:63], v[62:63], v[4:5]
	v_rcp_iflag_f32_e32 v4, v2
	v_cvt_f32_ubyte1_e32 v2, v164
	v_rcp_iflag_f32_e32 v5, v2
	v_pk_mul_f32 v[68:69], v[68:69], v[186:187]
	v_cvt_f32_ubyte3_e32 v187, v159
	v_cvt_f32_ubyte2_e32 v186, v159
	v_pk_mul_f32 v[158:159], v[162:163], v[186:187]
	v_cvt_f32_ubyte2_e32 v2, v164
	v_pk_mul_f32 v[64:65], v[64:65], v[158:159]
	v_rcp_iflag_f32_e32 v158, v2
	v_cvt_f32_ubyte3_e32 v2, v164
	v_cvt_f32_ubyte1_e32 v187, v160
	v_cvt_f32_ubyte0_e32 v186, v160
	v_rcp_iflag_f32_e32 v159, v2
	v_pk_mul_f32 v[4:5], v[4:5], v[186:187]
	v_cvt_f32_ubyte0_e32 v2, v165
	v_pk_mul_f32 v[58:59], v[58:59], v[4:5]
	v_rcp_iflag_f32_e32 v4, v2
	v_cvt_f32_ubyte1_e32 v2, v165
	v_rcp_iflag_f32_e32 v5, v2
	v_cvt_f32_ubyte3_e32 v163, v160
	v_cvt_f32_ubyte2_e32 v162, v160
	v_pk_mul_f32 v[158:159], v[158:159], v[162:163]
	v_cvt_f32_ubyte2_e32 v2, v165
	v_pk_mul_f32 v[60:61], v[60:61], v[158:159]
	v_rcp_iflag_f32_e32 v158, v2
	v_cvt_f32_ubyte3_e32 v2, v165
	v_cvt_f32_ubyte1_e32 v165, v161
	v_cvt_f32_ubyte0_e32 v164, v161
	v_rcp_iflag_f32_e32 v159, v2
	v_pk_mul_f32 v[4:5], v[4:5], v[164:165]
	v_cvt_f32_ubyte0_e32 v2, v154
	v_pk_mul_f32 v[54:55], v[54:55], v[4:5]
	v_rcp_iflag_f32_e32 v4, v2
	v_cvt_f32_ubyte1_e32 v2, v154
	v_rcp_iflag_f32_e32 v5, v2
	v_cvt_f32_ubyte3_e32 v163, v161
	v_cvt_f32_ubyte2_e32 v162, v161
	v_pk_mul_f32 v[158:159], v[158:159], v[162:163]
	v_cvt_f32_ubyte2_e32 v2, v154
	v_pk_mul_f32 v[56:57], v[56:57], v[158:159]
	v_rcp_iflag_f32_e32 v158, v2
	v_cvt_f32_ubyte3_e32 v2, v154
	v_cvt_f32_ubyte1_e32 v163, v150
	v_cvt_f32_ubyte0_e32 v162, v150
	v_rcp_iflag_f32_e32 v159, v2
	v_pk_mul_f32 v[4:5], v[4:5], v[162:163]
	v_cvt_f32_ubyte0_e32 v2, v155
	v_pk_mul_f32 v[50:51], v[50:51], v[4:5]
	v_rcp_iflag_f32_e32 v4, v2
	v_cvt_f32_ubyte1_e32 v2, v155
	v_rcp_iflag_f32_e32 v5, v2
	v_cvt_f32_ubyte3_e32 v161, v150
	v_cvt_f32_ubyte2_e32 v160, v150
	v_cvt_f32_ubyte2_e32 v2, v155
	v_pk_mul_f32 v[158:159], v[158:159], v[160:161]
	v_rcp_iflag_f32_e32 v154, v2
	v_cvt_f32_ubyte3_e32 v2, v155
	v_cvt_f32_ubyte1_e32 v161, v151
	v_cvt_f32_ubyte0_e32 v160, v151
	v_rcp_iflag_f32_e32 v155, v2
	v_pk_mul_f32 v[4:5], v[4:5], v[160:161]
	v_cvt_f32_ubyte0_e32 v2, v156
	v_pk_mul_f32 v[46:47], v[46:47], v[4:5]
	v_rcp_iflag_f32_e32 v4, v2
	v_cvt_f32_ubyte1_e32 v2, v156
	v_rcp_iflag_f32_e32 v5, v2
	v_pk_mul_f32 v[52:53], v[52:53], v[158:159]
	v_cvt_f32_ubyte3_e32 v159, v151
	v_cvt_f32_ubyte2_e32 v158, v151
	v_pk_mul_f32 v[150:151], v[154:155], v[158:159]
	v_cvt_f32_ubyte2_e32 v2, v156
	v_pk_mul_f32 v[48:49], v[48:49], v[150:151]
	v_rcp_iflag_f32_e32 v150, v2
	v_cvt_f32_ubyte3_e32 v2, v156
	v_cvt_f32_ubyte1_e32 v159, v152
	v_cvt_f32_ubyte0_e32 v158, v152
	v_rcp_iflag_f32_e32 v151, v2
	v_pk_mul_f32 v[4:5], v[4:5], v[158:159]
	v_cvt_f32_ubyte0_e32 v2, v157
	v_pk_mul_f32 v[42:43], v[42:43], v[4:5]
	v_rcp_iflag_f32_e32 v4, v2
	v_cvt_f32_ubyte1_e32 v2, v157
	v_rcp_iflag_f32_e32 v5, v2
	v_cvt_f32_ubyte3_e32 v155, v152
	v_cvt_f32_ubyte2_e32 v154, v152
	v_pk_mul_f32 v[150:151], v[150:151], v[154:155]
	v_cvt_f32_ubyte2_e32 v2, v157
	v_pk_mul_f32 v[44:45], v[44:45], v[150:151]
	v_rcp_iflag_f32_e32 v150, v2
	v_cvt_f32_ubyte3_e32 v2, v157
	v_cvt_f32_ubyte1_e32 v157, v153
	v_cvt_f32_ubyte0_e32 v156, v153
	v_rcp_iflag_f32_e32 v151, v2
	v_pk_mul_f32 v[4:5], v[4:5], v[156:157]
	v_cvt_f32_ubyte0_e32 v2, v146
	v_pk_mul_f32 v[38:39], v[38:39], v[4:5]
	v_rcp_iflag_f32_e32 v4, v2
	v_cvt_f32_ubyte1_e32 v2, v146
	v_rcp_iflag_f32_e32 v5, v2
	v_cvt_f32_ubyte3_e32 v155, v153
	v_cvt_f32_ubyte2_e32 v154, v153
	v_pk_mul_f32 v[150:151], v[150:151], v[154:155]
	v_cvt_f32_ubyte2_e32 v2, v146
	v_pk_mul_f32 v[40:41], v[40:41], v[150:151]
	v_rcp_iflag_f32_e32 v150, v2
	v_cvt_f32_ubyte3_e32 v2, v146
	v_cvt_f32_ubyte1_e32 v155, v142
	v_cvt_f32_ubyte0_e32 v154, v142
	v_rcp_iflag_f32_e32 v151, v2
	v_pk_mul_f32 v[4:5], v[4:5], v[154:155]
	v_cvt_f32_ubyte0_e32 v2, v147
	v_pk_mul_f32 v[34:35], v[34:35], v[4:5]
	v_rcp_iflag_f32_e32 v4, v2
	v_cvt_f32_ubyte1_e32 v2, v147
	v_rcp_iflag_f32_e32 v5, v2
	v_cvt_f32_ubyte3_e32 v153, v142
	v_cvt_f32_ubyte2_e32 v152, v142
	v_cvt_f32_ubyte2_e32 v2, v147
	v_pk_mul_f32 v[150:151], v[150:151], v[152:153]
	v_rcp_iflag_f32_e32 v146, v2
	v_cvt_f32_ubyte3_e32 v2, v147
	v_cvt_f32_ubyte1_e32 v153, v143
	v_cvt_f32_ubyte0_e32 v152, v143
	v_rcp_iflag_f32_e32 v147, v2
	v_pk_mul_f32 v[4:5], v[4:5], v[152:153]
	v_cvt_f32_ubyte0_e32 v2, v148
	v_pk_mul_f32 v[30:31], v[30:31], v[4:5]
	v_rcp_iflag_f32_e32 v4, v2
	v_cvt_f32_ubyte1_e32 v2, v148
	v_rcp_iflag_f32_e32 v5, v2
	v_pk_mul_f32 v[36:37], v[36:37], v[150:151]
	v_cvt_f32_ubyte3_e32 v151, v143
	v_cvt_f32_ubyte2_e32 v150, v143
	v_pk_mul_f32 v[142:143], v[146:147], v[150:151]
	v_cvt_f32_ubyte2_e32 v2, v148
	v_pk_mul_f32 v[32:33], v[32:33], v[142:143]
	v_rcp_iflag_f32_e32 v142, v2
	v_cvt_f32_ubyte3_e32 v2, v148
	v_cvt_f32_ubyte1_e32 v151, v144
	v_cvt_f32_ubyte0_e32 v150, v144
	v_rcp_iflag_f32_e32 v143, v2
	v_pk_mul_f32 v[4:5], v[4:5], v[150:151]
	v_cvt_f32_ubyte0_e32 v2, v149
	v_pk_mul_f32 v[26:27], v[26:27], v[4:5]
	v_rcp_iflag_f32_e32 v4, v2
	v_cvt_f32_ubyte1_e32 v2, v149
	v_rcp_iflag_f32_e32 v5, v2
	v_cvt_f32_ubyte3_e32 v147, v144
	v_cvt_f32_ubyte2_e32 v146, v144
	v_pk_mul_f32 v[142:143], v[142:143], v[146:147]
	v_cvt_f32_ubyte2_e32 v2, v149
	v_pk_mul_f32 v[28:29], v[28:29], v[142:143]
	v_rcp_iflag_f32_e32 v142, v2
	v_cvt_f32_ubyte3_e32 v2, v149
	v_cvt_f32_ubyte1_e32 v149, v145
	v_cvt_f32_ubyte0_e32 v148, v145
	v_rcp_iflag_f32_e32 v143, v2
	v_pk_mul_f32 v[4:5], v[4:5], v[148:149]
	s_waitcnt vmcnt(0)
	v_cvt_f32_ubyte0_e32 v2, v138
	v_pk_mul_f32 v[22:23], v[22:23], v[4:5]
	v_rcp_iflag_f32_e32 v4, v2
	v_cvt_f32_ubyte1_e32 v2, v138
	v_rcp_iflag_f32_e32 v5, v2
	v_cvt_f32_ubyte3_e32 v147, v145
	v_cvt_f32_ubyte2_e32 v146, v145
	v_pk_mul_f32 v[142:143], v[142:143], v[146:147]
	v_cvt_f32_ubyte2_e32 v2, v138
	v_pk_mul_f32 v[24:25], v[24:25], v[142:143]
	v_rcp_iflag_f32_e32 v142, v2
	v_cvt_f32_ubyte3_e32 v2, v138
	v_cvt_f32_ubyte1_e32 v147, v134
	v_cvt_f32_ubyte0_e32 v146, v134
	v_rcp_iflag_f32_e32 v143, v2
	v_pk_mul_f32 v[4:5], v[4:5], v[146:147]
	v_cvt_f32_ubyte0_e32 v2, v139
	v_pk_mul_f32 v[18:19], v[18:19], v[4:5]
	v_rcp_iflag_f32_e32 v4, v2
	v_cvt_f32_ubyte1_e32 v2, v139
	v_rcp_iflag_f32_e32 v5, v2
	v_cvt_f32_ubyte2_e32 v2, v139
	v_rcp_iflag_f32_e32 v138, v2
	v_cvt_f32_ubyte3_e32 v2, v139
	v_cvt_f32_ubyte3_e32 v145, v134
	v_cvt_f32_ubyte2_e32 v144, v134
	v_rcp_iflag_f32_e32 v139, v2
	v_pk_mul_f32 v[142:143], v[142:143], v[144:145]
	v_cvt_f32_ubyte1_e32 v145, v135
	v_cvt_f32_ubyte0_e32 v144, v135
	v_pk_mul_f32 v[4:5], v[4:5], v[144:145]
	v_cvt_f32_ubyte0_e32 v2, v140
	v_pk_mul_f32 v[20:21], v[20:21], v[142:143]
	v_cvt_f32_ubyte3_e32 v143, v135
	v_cvt_f32_ubyte2_e32 v142, v135
	v_pk_mul_f32 v[14:15], v[14:15], v[4:5]
	v_rcp_iflag_f32_e32 v4, v2
	v_cvt_f32_ubyte1_e32 v2, v140
	v_pk_mul_f32 v[134:135], v[138:139], v[142:143]
	v_rcp_iflag_f32_e32 v5, v2
	v_cvt_f32_ubyte2_e32 v2, v140
	v_pk_mul_f32 v[16:17], v[16:17], v[134:135]
	v_rcp_iflag_f32_e32 v134, v2
	v_cvt_f32_ubyte3_e32 v2, v140
	v_rcp_iflag_f32_e32 v135, v2
	v_cvt_f32_ubyte1_e32 v143, v136
	v_cvt_f32_ubyte0_e32 v142, v136
	v_pk_mul_f32 v[4:5], v[4:5], v[142:143]
	v_cvt_f32_ubyte0_e32 v2, v141
	v_cvt_f32_ubyte3_e32 v139, v136
	v_cvt_f32_ubyte2_e32 v138, v136
	v_pk_mul_f32 v[10:11], v[10:11], v[4:5]
	v_rcp_iflag_f32_e32 v4, v2
	v_cvt_f32_ubyte1_e32 v2, v141
	v_pk_mul_f32 v[134:135], v[134:135], v[138:139]
	v_rcp_iflag_f32_e32 v5, v2
	v_cvt_f32_ubyte2_e32 v2, v141
	v_pk_mul_f32 v[12:13], v[12:13], v[134:135]
	v_rcp_iflag_f32_e32 v134, v2
	v_cvt_f32_ubyte3_e32 v2, v141
	v_rcp_iflag_f32_e32 v135, v2
	v_cvt_f32_ubyte3_e32 v139, v137
	v_cvt_f32_ubyte2_e32 v138, v137
	v_cvt_f32_ubyte1_e32 v141, v137
	v_cvt_f32_ubyte0_e32 v140, v137
	v_pk_mul_f32 v[4:5], v[4:5], v[140:141]
	v_pk_mul_f32 v[134:135], v[134:135], v[138:139]
	v_pk_mul_f32 v[6:7], v[6:7], v[4:5]
	v_pk_mul_f32 v[8:9], v[8:9], v[134:135]
	s_cbranch_vccnz .LBB0_3768
	s_barrier

.LBB0_3773:
	s_add_i32 s18, s53, 32
	v_mov_b32_e32 v2, v182
	v_mov_b32_e32 v179, v183
	s_ashr_i32 s19, s18, 31
	s_lshl_b64 s[18:19], s[18:19], 16
	v_lshl_add_u32 v136, v179, 4, v2
	s_add_u32 s18, s36, s18
	v_add_u32_e32 v4, s39, v136
	s_addc_u32 s19, s37, s19
	v_ashrrev_i32_e32 v5, 31, v4
	v_lshl_add_u64 v[134:135], v[4:5], 4, s[18:19]
	global_load_dwordx4 v[162:165], v[134:135], off nt
	v_add_u32_e32 v4, 0x200, v4
	v_ashrrev_i32_e32 v5, 31, v4
	v_lshl_add_u64 v[4:5], v[4:5], 4, s[18:19]
	global_load_dwordx4 v[158:161], v[4:5], off nt
	v_add_u32_e32 v4, s40, v136
	v_ashrrev_i32_e32 v5, 31, v4
	v_lshl_add_u64 v[4:5], v[4:5], 4, s[18:19]
	global_load_dwordx4 v[154:157], v[4:5], off nt
	v_add_u32_e32 v4, s42, v136
	v_ashrrev_i32_e32 v5, 31, v4
	v_lshl_add_u64 v[4:5], v[4:5], 4, s[18:19]
	global_load_dwordx4 v[150:153], v[4:5], off nt
	v_add_u32_e32 v4, s43, v136
	v_ashrrev_i32_e32 v5, 31, v4
	v_lshl_add_u64 v[4:5], v[4:5], 4, s[18:19]
	global_load_dwordx4 v[146:149], v[4:5], off nt
	v_add_u32_e32 v4, s44, v136
	v_ashrrev_i32_e32 v5, 31, v4
	v_lshl_add_u64 v[4:5], v[4:5], 4, s[18:19]
	global_load_dwordx4 v[142:145], v[4:5], off nt
	v_add_u32_e32 v4, s45, v136
	v_ashrrev_i32_e32 v5, 31, v4
	v_lshl_add_u64 v[4:5], v[4:5], 4, s[18:19]
	global_load_dwordx4 v[138:141], v[4:5], off nt
	v_add_u32_e32 v4, s46, v136
	v_ashrrev_i32_e32 v5, 31, v4
	v_lshl_add_u64 v[4:5], v[4:5], 4, s[18:19]
	s_lshl_b32 s18, s52, 6
	s_lshl_b32 s15, s15, 2
	s_add_i32 s18, s18, s15
	s_or_b32 s15, s18, s47
	v_add_u32_e32 v178, s33, v2
	s_lshl_b32 s18, s15, 8
	global_load_dwordx4 v[134:137], v[4:5], off nt
	v_lshlrev_b32_e32 v4, 3, v179
	v_ashrrev_i32_e32 v179, 31, v178
	s_ashr_i32 s19, s18, 31
	v_ashrrev_i32_e32 v5, 31, v4
	v_lshl_add_u64 v[4:5], v[4:5], 1, s[12:13]
	s_or_b32 s20, s18, 0x200
	s_ashr_i32 s21, s20, 31
	s_and_b64 vcc, exec, s[4:5]
	s_movk_i32 s55, 0x1ff
	s_mov_b64 s[56:57], 0x10000
	s_waitcnt vmcnt(0)
	v_cvt_f32_ubyte1_e32 v181, v162
	v_cvt_f32_ubyte0_e32 v180, v162
	v_pk_mul_f32 v[180:181], v[180:181], s[78:79] op_sel_hi:[1,0]
	s_nop 0
	v_pk_mul_f32 v[130:131], v[130:131], v[180:181]
	v_cvt_f32_ubyte1_e32 v181, v163
	v_cvt_f32_ubyte0_e32 v180, v163
	v_pk_mul_f32 v[180:181], v[180:181], s[78:79] op_sel_hi:[1,0]
	s_nop 0
	v_pk_mul_f32 v[180:181], v[126:127], v[180:181]
	v_cvt_f32_ubyte3_e32 v127, v162
	v_cvt_f32_ubyte2_e32 v126, v162
	v_pk_mul_f32 v[126:127], v[126:127], s[78:79] op_sel_hi:[1,0]
	s_nop 0
	v_pk_mul_f32 v[132:133], v[132:133], v[126:127]
	v_cvt_f32_ubyte3_e32 v127, v163
	v_cvt_f32_ubyte2_e32 v126, v163
	v_pk_mul_f32 v[126:127], v[126:127], s[78:79] op_sel_hi:[1,0]
	s_nop 0
	v_pk_mul_f32 v[162:163], v[128:129], v[126:127]
	v_cvt_pk_bf16_f32 v126, v130, v131
	v_lshl_add_u64 v[130:131], v[178:179], 0, s[18:19]
	v_lshlrev_b64 v[130:131], 7, v[130:131]
	v_cvt_pk_bf16_f32 v127, v132, v133
	v_cvt_pk_bf16_f32 v128, v180, v181
	v_cvt_pk_bf16_f32 v129, v162, v163
	v_lshl_add_u64 v[130:131], v[4:5], 0, v[130:131]
	global_store_dwordx4 v[130:131], v[126:129], off
	s_nop 1
	v_cvt_f32_ubyte1_e32 v127, v164
	v_cvt_f32_ubyte0_e32 v126, v164
	v_pk_mul_f32 v[126:127], v[126:127], s[78:79] op_sel_hi:[1,0]
	s_nop 0
	v_pk_mul_f32 v[122:123], v[122:123], v[126:127]
	v_cvt_f32_ubyte1_e32 v127, v165
	v_cvt_f32_ubyte0_e32 v126, v165
	v_pk_mul_f32 v[126:127], v[126:127], s[78:79] op_sel_hi:[1,0]
	s_nop 0
	v_pk_mul_f32 v[126:127], v[118:119], v[126:127]
	v_cvt_f32_ubyte3_e32 v119, v164
	v_cvt_f32_ubyte2_e32 v118, v164
	v_pk_mul_f32 v[118:119], v[118:119], s[78:79] op_sel_hi:[1,0]
	s_nop 0
	v_pk_mul_f32 v[124:125], v[124:125], v[118:119]
	v_cvt_f32_ubyte3_e32 v119, v165
	v_cvt_f32_ubyte2_e32 v118, v165
	v_pk_mul_f32 v[118:119], v[118:119], s[78:79] op_sel_hi:[1,0]
	s_nop 0
	v_pk_mul_f32 v[128:129], v[120:121], v[118:119]
	v_cvt_pk_bf16_f32 v118, v122, v123
	v_lshl_add_u64 v[122:123], v[178:179], 0, s[20:21]
	v_lshlrev_b64 v[122:123], 7, v[122:123]
	v_cvt_pk_bf16_f32 v119, v124, v125
	v_cvt_pk_bf16_f32 v120, v126, v127
	v_cvt_pk_bf16_f32 v121, v128, v129
	v_lshl_add_u64 v[122:123], v[4:5], 0, v[122:123]
	global_store_dwordx4 v[122:123], v[118:121], off
	s_nop 1
	v_cvt_f32_ubyte1_e32 v121, v158
	v_cvt_f32_ubyte0_e32 v120, v158
	v_pk_mul_f32 v[120:121], v[120:121], s[78:79] op_sel_hi:[1,0]
	v_add_u32_e32 v118, 16, v178
	v_pk_mul_f32 v[114:115], v[114:115], v[120:121]
	v_cvt_f32_ubyte1_e32 v121, v159
	v_cvt_f32_ubyte0_e32 v120, v159
	v_pk_mul_f32 v[120:121], v[120:121], s[78:79] op_sel_hi:[1,0]
	v_ashrrev_i32_e32 v119, 31, v118
	v_pk_mul_f32 v[120:121], v[110:111], v[120:121]
	v_cvt_f32_ubyte3_e32 v111, v158
	v_cvt_f32_ubyte2_e32 v110, v158
	v_pk_mul_f32 v[110:111], v[110:111], s[78:79] op_sel_hi:[1,0]
	s_nop 0
	v_pk_mul_f32 v[116:117], v[116:117], v[110:111]
	v_cvt_f32_ubyte3_e32 v111, v159
	v_cvt_f32_ubyte2_e32 v110, v159
	v_pk_mul_f32 v[110:111], v[110:111], s[78:79] op_sel_hi:[1,0]
	s_nop 0
	v_pk_mul_f32 v[122:123], v[112:113], v[110:111]
	v_cvt_pk_bf16_f32 v110, v114, v115
	v_lshl_add_u64 v[114:115], v[118:119], 0, s[18:19]
	v_lshlrev_b64 v[114:115], 7, v[114:115]
	v_cvt_pk_bf16_f32 v111, v116, v117
	v_cvt_pk_bf16_f32 v112, v120, v121
	v_cvt_pk_bf16_f32 v113, v122, v123
	v_lshl_add_u64 v[114:115], v[4:5], 0, v[114:115]
	global_store_dwordx4 v[114:115], v[110:113], off
	s_nop 1
	v_cvt_f32_ubyte1_e32 v111, v160
	v_cvt_f32_ubyte0_e32 v110, v160
	v_pk_mul_f32 v[110:111], v[110:111], s[78:79] op_sel_hi:[1,0]
	s_nop 0
	v_pk_mul_f32 v[106:107], v[106:107], v[110:111]
	v_cvt_f32_ubyte1_e32 v111, v161
	v_cvt_f32_ubyte0_e32 v110, v161
	v_pk_mul_f32 v[110:111], v[110:111], s[78:79] op_sel_hi:[1,0]
	s_nop 0
	v_pk_mul_f32 v[110:111], v[102:103], v[110:111]
	v_cvt_f32_ubyte3_e32 v103, v160
	v_cvt_f32_ubyte2_e32 v102, v160
	v_pk_mul_f32 v[102:103], v[102:103], s[78:79] op_sel_hi:[1,0]
	s_nop 0
	v_pk_mul_f32 v[108:109], v[108:109], v[102:103]
	v_cvt_f32_ubyte3_e32 v103, v161
	v_cvt_f32_ubyte2_e32 v102, v161
	v_pk_mul_f32 v[102:103], v[102:103], s[78:79] op_sel_hi:[1,0]
	s_nop 0
	v_pk_mul_f32 v[112:113], v[104:105], v[102:103]
	v_cvt_pk_bf16_f32 v102, v106, v107
	v_lshl_add_u64 v[106:107], v[118:119], 0, s[20:21]
	v_lshlrev_b64 v[106:107], 7, v[106:107]
	v_cvt_pk_bf16_f32 v103, v108, v109
	v_cvt_pk_bf16_f32 v104, v110, v111
	v_cvt_pk_bf16_f32 v105, v112, v113
	v_lshl_add_u64 v[106:107], v[4:5], 0, v[106:107]
	global_store_dwordx4 v[106:107], v[102:105], off
	s_nop 1
	v_cvt_f32_ubyte1_e32 v105, v154
	v_cvt_f32_ubyte0_e32 v104, v154
	v_pk_mul_f32 v[104:105], v[104:105], s[78:79] op_sel_hi:[1,0]
	v_add_u32_e32 v102, 32, v178
	v_pk_mul_f32 v[98:99], v[98:99], v[104:105]
	v_cvt_f32_ubyte1_e32 v105, v155
	v_cvt_f32_ubyte0_e32 v104, v155
	v_pk_mul_f32 v[104:105], v[104:105], s[78:79] op_sel_hi:[1,0]
	v_ashrrev_i32_e32 v103, 31, v102
	v_pk_mul_f32 v[104:105], v[94:95], v[104:105]
	v_cvt_f32_ubyte3_e32 v95, v154
	v_cvt_f32_ubyte2_e32 v94, v154
	v_pk_mul_f32 v[94:95], v[94:95], s[78:79] op_sel_hi:[1,0]
	s_nop 0
	v_pk_mul_f32 v[100:101], v[100:101], v[94:95]
	v_cvt_f32_ubyte3_e32 v95, v155
	v_cvt_f32_ubyte2_e32 v94, v155
	v_pk_mul_f32 v[94:95], v[94:95], s[78:79] op_sel_hi:[1,0]
	s_nop 0
	v_pk_mul_f32 v[106:107], v[96:97], v[94:95]
	v_cvt_pk_bf16_f32 v94, v98, v99
	v_lshl_add_u64 v[98:99], v[102:103], 0, s[18:19]
	v_lshlrev_b64 v[98:99], 7, v[98:99]
	v_cvt_pk_bf16_f32 v95, v100, v101
	v_cvt_pk_bf16_f32 v96, v104, v105
	v_cvt_pk_bf16_f32 v97, v106, v107
	v_lshl_add_u64 v[98:99], v[4:5], 0, v[98:99]
	global_store_dwordx4 v[98:99], v[94:97], off
	s_nop 1
	v_cvt_f32_ubyte1_e32 v95, v156
	v_cvt_f32_ubyte0_e32 v94, v156
	v_pk_mul_f32 v[94:95], v[94:95], s[78:79] op_sel_hi:[1,0]
	s_nop 0
	v_pk_mul_f32 v[90:91], v[90:91], v[94:95]
	v_cvt_f32_ubyte1_e32 v95, v157
	v_cvt_f32_ubyte0_e32 v94, v157
	v_pk_mul_f32 v[94:95], v[94:95], s[78:79] op_sel_hi:[1,0]
	s_nop 0
	v_pk_mul_f32 v[94:95], v[86:87], v[94:95]
	v_cvt_f32_ubyte3_e32 v87, v156
	v_cvt_f32_ubyte2_e32 v86, v156
	v_pk_mul_f32 v[86:87], v[86:87], s[78:79] op_sel_hi:[1,0]
	s_nop 0
	v_pk_mul_f32 v[92:93], v[92:93], v[86:87]
	v_cvt_f32_ubyte3_e32 v87, v157
	v_cvt_f32_ubyte2_e32 v86, v157
	v_pk_mul_f32 v[86:87], v[86:87], s[78:79] op_sel_hi:[1,0]
	s_nop 0
	v_pk_mul_f32 v[96:97], v[88:89], v[86:87]
	v_cvt_pk_bf16_f32 v86, v90, v91
	v_lshl_add_u64 v[90:91], v[102:103], 0, s[20:21]
	v_lshlrev_b64 v[90:91], 7, v[90:91]
	v_cvt_pk_bf16_f32 v87, v92, v93
	v_cvt_pk_bf16_f32 v88, v94, v95
	v_cvt_pk_bf16_f32 v89, v96, v97
	v_lshl_add_u64 v[90:91], v[4:5], 0, v[90:91]
	global_store_dwordx4 v[90:91], v[86:89], off
	s_nop 1
	v_cvt_f32_ubyte1_e32 v89, v150
	v_cvt_f32_ubyte0_e32 v88, v150
	v_pk_mul_f32 v[88:89], v[88:89], s[78:79] op_sel_hi:[1,0]
	v_add_u32_e32 v86, 48, v178
	v_pk_mul_f32 v[82:83], v[82:83], v[88:89]
	v_cvt_f32_ubyte1_e32 v89, v151
	v_cvt_f32_ubyte0_e32 v88, v151
	v_pk_mul_f32 v[88:89], v[88:89], s[78:79] op_sel_hi:[1,0]
	v_ashrrev_i32_e32 v87, 31, v86
	v_pk_mul_f32 v[88:89], v[78:79], v[88:89]
	v_cvt_f32_ubyte3_e32 v79, v150
	v_cvt_f32_ubyte2_e32 v78, v150
	v_pk_mul_f32 v[78:79], v[78:79], s[78:79] op_sel_hi:[1,0]
	s_nop 0
	v_pk_mul_f32 v[84:85], v[84:85], v[78:79]
	v_cvt_f32_ubyte3_e32 v79, v151
	v_cvt_f32_ubyte2_e32 v78, v151
	v_pk_mul_f32 v[78:79], v[78:79], s[78:79] op_sel_hi:[1,0]
	s_nop 0
	v_pk_mul_f32 v[90:91], v[80:81], v[78:79]
	v_cvt_pk_bf16_f32 v78, v82, v83
	v_lshl_add_u64 v[82:83], v[86:87], 0, s[18:19]
	v_lshlrev_b64 v[82:83], 7, v[82:83]
	v_cvt_pk_bf16_f32 v79, v84, v85
	v_cvt_pk_bf16_f32 v80, v88, v89
	v_cvt_pk_bf16_f32 v81, v90, v91
	v_lshl_add_u64 v[82:83], v[4:5], 0, v[82:83]
	global_store_dwordx4 v[82:83], v[78:81], off
	s_nop 1
	v_cvt_f32_ubyte1_e32 v79, v152
	v_cvt_f32_ubyte0_e32 v78, v152
	v_pk_mul_f32 v[78:79], v[78:79], s[78:79] op_sel_hi:[1,0]
	s_nop 0
	v_pk_mul_f32 v[74:75], v[74:75], v[78:79]
	v_cvt_f32_ubyte1_e32 v79, v153
	v_cvt_f32_ubyte0_e32 v78, v153
	v_pk_mul_f32 v[78:79], v[78:79], s[78:79] op_sel_hi:[1,0]
	s_nop 0
	v_pk_mul_f32 v[78:79], v[70:71], v[78:79]
	v_cvt_f32_ubyte3_e32 v71, v152
	v_cvt_f32_ubyte2_e32 v70, v152
	v_pk_mul_f32 v[70:71], v[70:71], s[78:79] op_sel_hi:[1,0]
	s_nop 0
	v_pk_mul_f32 v[76:77], v[76:77], v[70:71]
	v_cvt_f32_ubyte3_e32 v71, v153
	v_cvt_f32_ubyte2_e32 v70, v153
	v_pk_mul_f32 v[70:71], v[70:71], s[78:79] op_sel_hi:[1,0]
	s_nop 0
	v_pk_mul_f32 v[80:81], v[72:73], v[70:71]
	v_cvt_pk_bf16_f32 v70, v74, v75
	v_lshl_add_u64 v[74:75], v[86:87], 0, s[20:21]
	v_lshlrev_b64 v[74:75], 7, v[74:75]
	v_cvt_pk_bf16_f32 v71, v76, v77
	v_cvt_pk_bf16_f32 v72, v78, v79
	v_cvt_pk_bf16_f32 v73, v80, v81
	v_lshl_add_u64 v[74:75], v[4:5], 0, v[74:75]
	global_store_dwordx4 v[74:75], v[70:73], off
	s_nop 1
	v_cvt_f32_ubyte1_e32 v73, v146
	v_cvt_f32_ubyte0_e32 v72, v146
	v_pk_mul_f32 v[72:73], v[72:73], s[78:79] op_sel_hi:[1,0]
	v_add_u32_e32 v70, 0x80, v178
	v_pk_mul_f32 v[66:67], v[66:67], v[72:73]
	v_cvt_f32_ubyte1_e32 v73, v147
	v_cvt_f32_ubyte0_e32 v72, v147
	v_pk_mul_f32 v[72:73], v[72:73], s[78:79] op_sel_hi:[1,0]
	v_ashrrev_i32_e32 v71, 31, v70
	v_pk_mul_f32 v[72:73], v[62:63], v[72:73]
	v_cvt_f32_ubyte3_e32 v63, v146
	v_cvt_f32_ubyte2_e32 v62, v146
	v_pk_mul_f32 v[62:63], v[62:63], s[78:79] op_sel_hi:[1,0]
	s_nop 0
	v_pk_mul_f32 v[68:69], v[68:69], v[62:63]
	v_cvt_f32_ubyte3_e32 v63, v147
	v_cvt_f32_ubyte2_e32 v62, v147
	v_pk_mul_f32 v[62:63], v[62:63], s[78:79] op_sel_hi:[1,0]
	s_nop 0
	v_pk_mul_f32 v[74:75], v[64:65], v[62:63]
	v_cvt_pk_bf16_f32 v62, v66, v67
	v_lshl_add_u64 v[66:67], v[70:71], 0, s[18:19]
	v_lshlrev_b64 v[66:67], 7, v[66:67]
	v_cvt_pk_bf16_f32 v63, v68, v69
	v_cvt_pk_bf16_f32 v64, v72, v73
	v_cvt_pk_bf16_f32 v65, v74, v75
	v_lshl_add_u64 v[66:67], v[4:5], 0, v[66:67]
	global_store_dwordx4 v[66:67], v[62:65], off
	s_nop 1
	v_cvt_f32_ubyte1_e32 v63, v148
	v_cvt_f32_ubyte0_e32 v62, v148
	v_pk_mul_f32 v[62:63], v[62:63], s[78:79] op_sel_hi:[1,0]
	s_nop 0
	v_pk_mul_f32 v[58:59], v[58:59], v[62:63]
	v_cvt_f32_ubyte1_e32 v63, v149
	v_cvt_f32_ubyte0_e32 v62, v149
	v_pk_mul_f32 v[62:63], v[62:63], s[78:79] op_sel_hi:[1,0]
	s_nop 0
	v_pk_mul_f32 v[62:63], v[54:55], v[62:63]
	v_cvt_f32_ubyte3_e32 v55, v148
	v_cvt_f32_ubyte2_e32 v54, v148
	v_pk_mul_f32 v[54:55], v[54:55], s[78:79] op_sel_hi:[1,0]
	s_nop 0
	v_pk_mul_f32 v[60:61], v[60:61], v[54:55]
	v_cvt_f32_ubyte3_e32 v55, v149
	v_cvt_f32_ubyte2_e32 v54, v149
	v_pk_mul_f32 v[54:55], v[54:55], s[78:79] op_sel_hi:[1,0]
	s_nop 0
	v_pk_mul_f32 v[64:65], v[56:57], v[54:55]
	v_cvt_pk_bf16_f32 v54, v58, v59
	v_lshl_add_u64 v[58:59], v[70:71], 0, s[20:21]
	v_lshlrev_b64 v[58:59], 7, v[58:59]
	v_cvt_pk_bf16_f32 v55, v60, v61
	v_cvt_pk_bf16_f32 v56, v62, v63
	v_cvt_pk_bf16_f32 v57, v64, v65
	v_lshl_add_u64 v[58:59], v[4:5], 0, v[58:59]
	global_store_dwordx4 v[58:59], v[54:57], off
	s_nop 1
	v_cvt_f32_ubyte1_e32 v57, v142
	v_cvt_f32_ubyte0_e32 v56, v142
	v_pk_mul_f32 v[56:57], v[56:57], s[78:79] op_sel_hi:[1,0]
	v_add_u32_e32 v54, 0x90, v178
	v_pk_mul_f32 v[50:51], v[50:51], v[56:57]
	v_cvt_f32_ubyte1_e32 v57, v143
	v_cvt_f32_ubyte0_e32 v56, v143
	v_pk_mul_f32 v[56:57], v[56:57], s[78:79] op_sel_hi:[1,0]
	v_ashrrev_i32_e32 v55, 31, v54
	v_pk_mul_f32 v[56:57], v[46:47], v[56:57]
	v_cvt_f32_ubyte3_e32 v47, v142
	v_cvt_f32_ubyte2_e32 v46, v142
	v_pk_mul_f32 v[46:47], v[46:47], s[78:79] op_sel_hi:[1,0]
	s_nop 0
	v_pk_mul_f32 v[52:53], v[52:53], v[46:47]
	v_cvt_f32_ubyte3_e32 v47, v143
	v_cvt_f32_ubyte2_e32 v46, v143
	v_pk_mul_f32 v[46:47], v[46:47], s[78:79] op_sel_hi:[1,0]
	s_nop 0
	v_pk_mul_f32 v[58:59], v[48:49], v[46:47]
	v_cvt_pk_bf16_f32 v46, v50, v51
	v_lshl_add_u64 v[50:51], v[54:55], 0, s[18:19]
	v_lshlrev_b64 v[50:51], 7, v[50:51]
	v_cvt_pk_bf16_f32 v47, v52, v53
	v_cvt_pk_bf16_f32 v48, v56, v57
	v_cvt_pk_bf16_f32 v49, v58, v59
	v_lshl_add_u64 v[50:51], v[4:5], 0, v[50:51]
	global_store_dwordx4 v[50:51], v[46:49], off
	s_nop 1
	v_cvt_f32_ubyte1_e32 v47, v144
	v_cvt_f32_ubyte0_e32 v46, v144
	v_pk_mul_f32 v[46:47], v[46:47], s[78:79] op_sel_hi:[1,0]
	s_nop 0
	v_pk_mul_f32 v[42:43], v[42:43], v[46:47]
	v_cvt_f32_ubyte1_e32 v47, v145
	v_cvt_f32_ubyte0_e32 v46, v145
	v_pk_mul_f32 v[46:47], v[46:47], s[78:79] op_sel_hi:[1,0]
	s_nop 0
	v_pk_mul_f32 v[46:47], v[38:39], v[46:47]
	v_cvt_f32_ubyte3_e32 v39, v144
	v_cvt_f32_ubyte2_e32 v38, v144
	v_pk_mul_f32 v[38:39], v[38:39], s[78:79] op_sel_hi:[1,0]
	s_nop 0
	v_pk_mul_f32 v[44:45], v[44:45], v[38:39]
	v_cvt_f32_ubyte3_e32 v39, v145
	v_cvt_f32_ubyte2_e32 v38, v145
	v_pk_mul_f32 v[38:39], v[38:39], s[78:79] op_sel_hi:[1,0]
	s_nop 0
	v_pk_mul_f32 v[48:49], v[40:41], v[38:39]
	v_cvt_pk_bf16_f32 v38, v42, v43
	v_lshl_add_u64 v[42:43], v[54:55], 0, s[20:21]
	v_lshlrev_b64 v[42:43], 7, v[42:43]
	v_cvt_pk_bf16_f32 v39, v44, v45
	v_cvt_pk_bf16_f32 v40, v46, v47
	v_cvt_pk_bf16_f32 v41, v48, v49
	v_lshl_add_u64 v[42:43], v[4:5], 0, v[42:43]
	global_store_dwordx4 v[42:43], v[38:41], off
	s_nop 1
	v_cvt_f32_ubyte1_e32 v41, v138
	v_cvt_f32_ubyte0_e32 v40, v138
	v_pk_mul_f32 v[40:41], v[40:41], s[78:79] op_sel_hi:[1,0]
	v_add_u32_e32 v38, 0xa0, v178
	v_pk_mul_f32 v[34:35], v[34:35], v[40:41]
	v_cvt_f32_ubyte1_e32 v41, v139
	v_cvt_f32_ubyte0_e32 v40, v139
	v_pk_mul_f32 v[40:41], v[40:41], s[78:79] op_sel_hi:[1,0]
	v_ashrrev_i32_e32 v39, 31, v38
	v_pk_mul_f32 v[40:41], v[30:31], v[40:41]
	v_cvt_f32_ubyte3_e32 v31, v138
	v_cvt_f32_ubyte2_e32 v30, v138
	v_pk_mul_f32 v[30:31], v[30:31], s[78:79] op_sel_hi:[1,0]
	s_nop 0
	v_pk_mul_f32 v[36:37], v[36:37], v[30:31]
	v_cvt_f32_ubyte3_e32 v31, v139
	v_cvt_f32_ubyte2_e32 v30, v139
	v_pk_mul_f32 v[30:31], v[30:31], s[78:79] op_sel_hi:[1,0]
	s_nop 0
	v_pk_mul_f32 v[42:43], v[32:33], v[30:31]
	v_cvt_pk_bf16_f32 v30, v34, v35
	v_lshl_add_u64 v[34:35], v[38:39], 0, s[18:19]
	v_lshlrev_b64 v[34:35], 7, v[34:35]
	v_cvt_pk_bf16_f32 v31, v36, v37
	v_cvt_pk_bf16_f32 v32, v40, v41
	v_cvt_pk_bf16_f32 v33, v42, v43
	v_lshl_add_u64 v[34:35], v[4:5], 0, v[34:35]
	global_store_dwordx4 v[34:35], v[30:33], off
	s_nop 1
	v_cvt_f32_ubyte1_e32 v31, v140
	v_cvt_f32_ubyte0_e32 v30, v140
	v_pk_mul_f32 v[30:31], v[30:31], s[78:79] op_sel_hi:[1,0]
	s_nop 0
	v_pk_mul_f32 v[26:27], v[26:27], v[30:31]
	v_cvt_f32_ubyte1_e32 v31, v141
	v_cvt_f32_ubyte0_e32 v30, v141
	v_pk_mul_f32 v[30:31], v[30:31], s[78:79] op_sel_hi:[1,0]
	s_nop 0
	v_pk_mul_f32 v[30:31], v[22:23], v[30:31]
	v_cvt_f32_ubyte3_e32 v23, v140
	v_cvt_f32_ubyte2_e32 v22, v140
	v_pk_mul_f32 v[22:23], v[22:23], s[78:79] op_sel_hi:[1,0]
	s_nop 0
	v_pk_mul_f32 v[28:29], v[28:29], v[22:23]
	v_cvt_f32_ubyte3_e32 v23, v141
	v_cvt_f32_ubyte2_e32 v22, v141
	v_pk_mul_f32 v[22:23], v[22:23], s[78:79] op_sel_hi:[1,0]
	s_nop 0
	v_pk_mul_f32 v[32:33], v[24:25], v[22:23]
	v_cvt_pk_bf16_f32 v22, v26, v27
	v_lshl_add_u64 v[26:27], v[38:39], 0, s[20:21]
	v_lshlrev_b64 v[26:27], 7, v[26:27]
	v_cvt_pk_bf16_f32 v23, v28, v29
	v_cvt_pk_bf16_f32 v24, v30, v31
	v_cvt_pk_bf16_f32 v25, v32, v33
	v_lshl_add_u64 v[26:27], v[4:5], 0, v[26:27]
	global_store_dwordx4 v[26:27], v[22:25], off
	s_nop 1
	v_cvt_f32_ubyte1_e32 v25, v134
	v_cvt_f32_ubyte0_e32 v24, v134
	v_pk_mul_f32 v[24:25], v[24:25], s[78:79] op_sel_hi:[1,0]
	v_add_u32_e32 v22, 0xb0, v178
	v_pk_mul_f32 v[18:19], v[18:19], v[24:25]
	v_cvt_f32_ubyte1_e32 v25, v135
	v_cvt_f32_ubyte0_e32 v24, v135
	v_pk_mul_f32 v[24:25], v[24:25], s[78:79] op_sel_hi:[1,0]
	v_ashrrev_i32_e32 v23, 31, v22
	v_pk_mul_f32 v[24:25], v[14:15], v[24:25]
	v_cvt_f32_ubyte3_e32 v15, v134
	v_cvt_f32_ubyte2_e32 v14, v134
	v_pk_mul_f32 v[14:15], v[14:15], s[78:79] op_sel_hi:[1,0]
	s_nop 0
	v_pk_mul_f32 v[20:21], v[20:21], v[14:15]
	v_cvt_f32_ubyte3_e32 v15, v135
	v_cvt_f32_ubyte2_e32 v14, v135
	v_pk_mul_f32 v[14:15], v[14:15], s[78:79] op_sel_hi:[1,0]
	s_nop 0
	v_pk_mul_f32 v[26:27], v[16:17], v[14:15]
	v_cvt_pk_bf16_f32 v14, v18, v19
	v_lshl_add_u64 v[18:19], v[22:23], 0, s[18:19]
	v_lshlrev_b64 v[18:19], 7, v[18:19]
	v_cvt_pk_bf16_f32 v15, v20, v21
	v_cvt_pk_bf16_f32 v16, v24, v25
	v_cvt_pk_bf16_f32 v17, v26, v27
	v_lshl_add_u64 v[18:19], v[4:5], 0, v[18:19]
	global_store_dwordx4 v[18:19], v[14:17], off
	s_mov_b64 s[18:19], -1
	s_nop 0
	v_cvt_f32_ubyte1_e32 v15, v136
	v_cvt_f32_ubyte0_e32 v14, v136
	v_pk_mul_f32 v[14:15], v[14:15], s[78:79] op_sel_hi:[1,0]
	s_nop 0
	v_pk_mul_f32 v[10:11], v[10:11], v[14:15]
	v_cvt_f32_ubyte1_e32 v15, v137
	v_cvt_f32_ubyte0_e32 v14, v137
	v_pk_mul_f32 v[14:15], v[14:15], s[78:79] op_sel_hi:[1,0]
	s_nop 0
	v_pk_mul_f32 v[14:15], v[6:7], v[14:15]
	v_cvt_f32_ubyte3_e32 v7, v136
	v_cvt_f32_ubyte2_e32 v6, v136
	v_pk_mul_f32 v[6:7], v[6:7], s[78:79] op_sel_hi:[1,0]
	s_nop 0
	v_pk_mul_f32 v[12:13], v[12:13], v[6:7]
	v_cvt_f32_ubyte3_e32 v7, v137
	v_cvt_f32_ubyte2_e32 v6, v137
	v_pk_mul_f32 v[6:7], v[6:7], s[78:79] op_sel_hi:[1,0]
	s_nop 0
	v_pk_mul_f32 v[16:17], v[8:9], v[6:7]
	v_cvt_pk_bf16_f32 v6, v10, v11
	v_lshl_add_u64 v[10:11], v[22:23], 0, s[20:21]
	v_lshlrev_b64 v[10:11], 7, v[10:11]
	v_cvt_pk_bf16_f32 v7, v12, v13
	v_cvt_pk_bf16_f32 v8, v14, v15
	v_cvt_pk_bf16_f32 v9, v16, v17
	v_lshl_add_u64 v[4:5], v[4:5], 0, v[10:11]
	global_store_dwordx4 v[4:5], v[6:9], off
	s_cbranch_vccnz .LBB0_3749
	s_andn2_b64 vcc, exec, s[8:9]
	s_cbranch_vccnz .LBB0_3748
	s_barrier
	s_branch .LBB0_3748
